# SSD masked-decay section: mask as one signed compare per element with 6 helper registers, plus the 16 decay values read from LDS once per chunk (was a read + full wait per element)
# speedup vs baseline: 1.0036x; 1.0036x over previous
; DI void ssd_item(const Params& p, int l, int it, char* smem) {
;     ...
;     __syncthreads();
; #pragma unroll
;     for (int ks = 4; ks < 8; ++ks) creg[ks] = *(const bf16x8*)(cr + ks * 16);
;     f32x16 acc[4], yd[2];
; #pragma unroll
;     for (int i = 0; i < 4; ++i)
; #pragma unroll
;       for (int r = 0; r < 16; ++r) acc[i][r] = 0.f;
; #pragma unroll
;     for (int i = 0; i < 2; ++i)
; #pragma unroll
;       for (int r = 0; r < 16; ++r) yd[i][r] = 0.f;
; #pragma unroll
;     for (int ks = 0; ks < 8; ++ks) {
;       const bf16x8 areg = creg[ks];
; #pragma unroll
;       for (int jb = 0; jb < 4; ++jb) {
;         const bf16x8 bb = *(const bf16x8*)&BG[(jb * 32 + l32) * 136 + ks * 16 + h * 8];
;         acc[jb] = __builtin_amdgcn_mfma_f32_32x32x16_bf16(areg, bb, acc[jb], 0, 0, 0);
;       }
;     }
.LBB0_996:
	s_or_b64 exec, exec, s[0:1]
	s_waitcnt lgkmcnt(0)
	s_barrier
	global_load_dwordx4 v[152:155], v[36:37], off offset:1664
	global_load_dwordx4 v[148:151], v[36:37], off offset:1696
	global_load_dwordx4 v[144:147], v[36:37], off offset:1728
	global_load_dwordx4 v[140:143], v[36:37], off offset:1760
	ds_read_b128 v[36:39], v197
	ds_read_b128 v[40:43], v197 offset:32
	s_waitcnt lgkmcnt(1)
	v_mfma_f32_32x32x16_bf16 v[112:127], v[32:35], v[36:39], 0
	ds_read_b128 v[36:39], v197 offset:8704
	v_lshlrev_b32_e32 v241, 16, v137
	v_lshlrev_b32_e32 v240, 16, v136
	v_lshlrev_b32_e32 v243, 16, v139
	v_lshlrev_b32_e32 v242, 16, v138
	ds_read_b32 v156, v239 offset:53760
	s_waitcnt lgkmcnt(0)
	v_pk_mul_f32 v[240:241], v[156:157], v[240:241] op_sel_hi:[0,1]
	v_mfma_f32_32x32x16_bf16 v[96:111], v[32:35], v[36:39], 0
	ds_read_b128 v[36:39], v197 offset:17408
	v_mul_f32_e64 v242, v156, v242
	v_mul_f32_e64 v243, v156, v243
	s_waitcnt lgkmcnt(0)
	v_mfma_f32_32x32x16_bf16 v[80:95], v[32:35], v[36:39], 0
	ds_read_b128 v[36:39], v197 offset:26112
	s_waitcnt lgkmcnt(0)
	v_mfma_f32_32x32x16_bf16 v[64:79], v[32:35], v[36:39], 0
	ds_read_b128 v[36:39], v197 offset:8736
	s_waitcnt lgkmcnt(0)
	v_mfma_f32_32x32x16_bf16 v[96:111], v[136:139], v[36:39], v[96:111]
	ds_read_b128 v[36:39], v197 offset:17440
	s_waitcnt lgkmcnt(0)
	v_mfma_f32_32x32x16_bf16 v[80:95], v[136:139], v[36:39], v[80:95]
	ds_read_b128 v[36:39], v197 offset:26144
	v_mfma_f32_32x32x16_bf16 v[112:127], v[136:139], v[40:43], v[112:127]
	s_waitcnt lgkmcnt(0)
	v_mfma_f32_32x32x16_bf16 v[64:79], v[136:139], v[36:39], v[64:79]
	ds_read_b128 v[36:39], v197 offset:64
	v_and_b32_e32 v137, 0xffff0000, v137
	v_and_b32_e32 v136, 0xffff0000, v136
	v_and_b32_e32 v139, 0xffff0000, v139
	v_and_b32_e32 v138, 0xffff0000, v138
	v_pk_mul_f32 v[136:137], v[156:157], v[136:137] op_sel_hi:[0,1]
	v_pk_mul_f32 v[138:139], v[156:157], v[138:139] op_sel_hi:[0,1]
	s_waitcnt lgkmcnt(0)
	v_mfma_f32_32x32x16_bf16 v[112:127], v[132:135], v[36:39], v[112:127]
	ds_read_b128 v[36:39], v197 offset:8768
	v_bfe_u32 v175, v139, 16, 1
	v_bfe_u32 v199, v138, 16, 1
	v_bfe_u32 v206, v137, 16, 1
	v_bfe_u32 v207, v136, 16, 1
	v_add3_u32 v136, v136, v207, s76
	v_add3_u32 v137, v137, v206, s76
	s_waitcnt lgkmcnt(0)
	v_mfma_f32_32x32x16_bf16 v[96:111], v[132:135], v[36:39], v[96:111]
	ds_read_b128 v[36:39], v197 offset:17472
	v_add3_u32 v138, v138, v199, s76
	v_add3_u32 v139, v139, v175, s76
	v_bfe_u32 v175, v240, 16, 1
	v_bfe_u32 v199, v241, 16, 1
	v_bfe_u32 v206, v242, 16, 1
	v_bfe_u32 v207, v243, 16, 1
	s_waitcnt lgkmcnt(0)
	v_mfma_f32_32x32x16_bf16 v[80:95], v[132:135], v[36:39], v[80:95]
	ds_read_b128 v[36:39], v197 offset:26176
	v_add3_u32 v207, v243, v207, s76
	v_add3_u32 v206, v242, v206, s76
	v_add3_u32 v199, v241, v199, s76
	v_add3_u32 v175, v240, v175, s76
	v_lshrrev_b32_e32 v175, 16, v175
	v_lshrrev_b32_e32 v199, 16, v199
	s_waitcnt lgkmcnt(0)
	v_mfma_f32_32x32x16_bf16 v[64:79], v[132:135], v[36:39], v[64:79]
	ds_read_b128 v[36:39], v197 offset:96
	v_lshrrev_b32_e32 v206, 16, v206
	v_lshrrev_b32_e32 v207, 16, v207
	v_and_or_b32 v139, v139, s77, v207
	v_and_or_b32 v138, v138, s77, v206
	v_and_or_b32 v137, v137, s77, v199
	v_and_or_b32 v136, v136, s77, v175
	s_waitcnt lgkmcnt(0)
	v_mfma_f32_32x32x16_bf16 v[112:127], v[128:131], v[36:39], v[112:127]
	ds_read_b128 v[36:39], v197 offset:8800
	ds_read_b128 v[240:243], v197 offset:34848
	s_waitcnt lgkmcnt(1)
	v_mfma_f32_32x32x16_bf16 v[96:111], v[128:131], v[36:39], v[96:111]
	ds_read_b128 v[36:39], v197 offset:17504
	s_waitcnt lgkmcnt(0)
	v_mfma_f32_32x32x16_bf16 v[80:95], v[128:131], v[36:39], v[80:95]
	ds_read_b128 v[36:39], v197 offset:26208
	s_waitcnt lgkmcnt(0)
	v_mfma_f32_32x32x16_bf16 v[64:79], v[128:131], v[36:39], v[64:79]
	ds_read_b128 v[36:39], v197 offset:128
	s_waitcnt vmcnt(3) lgkmcnt(0)
	v_mfma_f32_32x32x16_bf16 v[112:127], v[152:155], v[36:39], v[112:127]
	ds_read_b128 v[36:39], v197 offset:8832
	s_waitcnt lgkmcnt(0)
	v_mfma_f32_32x32x16_bf16 v[96:111], v[152:155], v[36:39], v[96:111]
	ds_read_b128 v[36:39], v197 offset:17536
	s_waitcnt lgkmcnt(0)
	v_mfma_f32_32x32x16_bf16 v[80:95], v[152:155], v[36:39], v[80:95]
	ds_read_b128 v[36:39], v197 offset:26240
	s_waitcnt lgkmcnt(0)
	v_mfma_f32_32x32x16_bf16 v[64:79], v[152:155], v[36:39], v[64:79]
	ds_read_b128 v[36:39], v197 offset:160
	s_waitcnt vmcnt(2) lgkmcnt(0)
	v_mfma_f32_32x32x16_bf16 v[112:127], v[148:151], v[36:39], v[112:127]
	ds_read_b128 v[36:39], v197 offset:8864
	s_waitcnt lgkmcnt(0)
	v_mfma_f32_32x32x16_bf16 v[96:111], v[148:151], v[36:39], v[96:111]
	ds_read_b128 v[36:39], v197 offset:17568
	s_waitcnt lgkmcnt(0)
	v_mfma_f32_32x32x16_bf16 v[80:95], v[148:151], v[36:39], v[80:95]
	ds_read_b128 v[36:39], v197 offset:26272
	s_waitcnt lgkmcnt(0)
	v_mfma_f32_32x32x16_bf16 v[64:79], v[148:151], v[36:39], v[64:79]
	ds_read_b128 v[36:39], v197 offset:192
	s_waitcnt vmcnt(1) lgkmcnt(0)
	v_mfma_f32_32x32x16_bf16 v[112:127], v[144:147], v[36:39], v[112:127]
	ds_read_b128 v[36:39], v197 offset:8896
	s_waitcnt lgkmcnt(0)
	v_mfma_f32_32x32x16_bf16 v[96:111], v[144:147], v[36:39], v[96:111]
	ds_read_b128 v[36:39], v197 offset:17600
	s_waitcnt lgkmcnt(0)
	v_mfma_f32_32x32x16_bf16 v[80:95], v[144:147], v[36:39], v[80:95]
	ds_read_b128 v[36:39], v197 offset:26304
	s_waitcnt lgkmcnt(0)
	v_mfma_f32_32x32x16_bf16 v[64:79], v[144:147], v[36:39], v[64:79]
	ds_read_b128 v[36:39], v197 offset:224
	s_waitcnt vmcnt(0) lgkmcnt(0)
	v_mfma_f32_32x32x16_bf16 v[112:127], v[140:143], v[36:39], v[112:127]
	ds_read_b128 v[36:39], v197 offset:8928
	s_waitcnt lgkmcnt(0)
	v_mfma_f32_32x32x16_bf16 v[96:111], v[140:143], v[36:39], v[96:111]
	ds_read_b128 v[36:39], v197 offset:17632
	s_waitcnt lgkmcnt(0)
; DI u32 pack2(float a, float b) { return (u32)f2bf(a) | ((u32)f2bf(b) << 16); }
; DI float bflo(u32 v) { return __uint_as_float(v << 16); }
; DI float bfhi(u32 v) { return __uint_as_float(v & 0xffff0000u); }
; DI void ssd_item(const Params& p, int l, int it, char* smem) {
;     ...
;     {
;       const float eai = fea[w * 32 + l32];
; #pragma unroll
;       for (int ks = 0; ks < 8; ++ks) {
;         union { u32 u[4]; bf16x8 v; } t;
;         t.v = creg[ks];
; #pragma unroll
;         for (int q = 0; q < 4; ++q) t.u[q] = pack2(bflo(t.u[q]) * eai, bfhi(t.u[q]) * eai);
; #pragma unroll
;         for (int pb = 0; pb < 2; ++pb) {
;           const bf16x8 bb = *(const bf16x8*)&HL[(pb * 32 + l32) * 136 + ks * 16 + h * 8];
;           yd[pb] = __builtin_amdgcn_mfma_f32_32x32x16_bf16(t.v, bb, yd[pb], 0, 0, 0);
;         }
;       }
;     }
	v_mfma_f32_32x32x16_bf16 v[80:95], v[140:143], v[36:39], v[80:95]
	ds_read_b128 v[36:39], v197 offset:26336
	s_waitcnt lgkmcnt(0)
	v_mfma_f32_32x32x16_bf16 v[64:79], v[140:143], v[36:39], v[64:79]
	v_lshlrev_b32_e32 v37, 16, v33
	v_lshlrev_b32_e32 v36, 16, v32
	v_and_b32_e32 v33, 0xffff0000, v33
	v_and_b32_e32 v32, 0xffff0000, v32
	v_lshlrev_b32_e32 v39, 16, v35
	v_lshlrev_b32_e32 v38, 16, v34
	v_and_b32_e32 v35, 0xffff0000, v35
	v_and_b32_e32 v34, 0xffff0000, v34
	v_pk_mul_f32 v[32:33], v[156:157], v[32:33] op_sel_hi:[0,1]
	v_pk_mul_f32 v[34:35], v[156:157], v[34:35] op_sel_hi:[0,1]
	v_pk_mul_f32 v[36:37], v[156:157], v[36:37] op_sel_hi:[0,1]
	v_pk_mul_f32 v[38:39], v[156:157], v[38:39] op_sel_hi:[0,1]
	v_bfe_u32 v40, v35, 16, 1
	v_bfe_u32 v41, v34, 16, 1
	v_bfe_u32 v42, v33, 16, 1
	v_bfe_u32 v43, v32, 16, 1
	v_add3_u32 v32, v32, v43, s76
	v_add3_u32 v33, v33, v42, s76
	v_add3_u32 v34, v34, v41, s76
	v_add3_u32 v35, v35, v40, s76
	v_bfe_u32 v40, v36, 16, 1
	v_bfe_u32 v41, v37, 16, 1
	v_bfe_u32 v42, v38, 16, 1
	v_bfe_u32 v43, v39, 16, 1
	v_add3_u32 v39, v39, v43, s76
	v_add3_u32 v38, v38, v42, s76
	v_add3_u32 v37, v37, v41, s76
	v_add3_u32 v36, v36, v40, s76
	v_lshrrev_b32_e32 v36, 16, v36
	v_lshrrev_b32_e32 v37, 16, v37
	v_lshrrev_b32_e32 v38, 16, v38
	v_lshrrev_b32_e32 v39, 16, v39
	v_and_or_b32 v35, v35, s77, v39
	v_and_or_b32 v34, v34, s77, v38
	v_and_or_b32 v33, v33, s77, v37
	v_and_or_b32 v32, v32, s77, v36
	ds_read_b128 v[36:39], v197 offset:34816
	s_waitcnt lgkmcnt(0)
	v_mfma_f32_32x32x16_bf16 v[48:63], v[32:35], v[36:39], 0
	ds_read_b128 v[36:39], v197 offset:43520
	v_mfma_f32_32x32x16_bf16 v[48:63], v[136:139], v[240:243], v[48:63]
	ds_read_b128 v[240:243], v197 offset:43552
	s_waitcnt lgkmcnt(1)
	v_mfma_f32_32x32x16_bf16 v[32:47], v[32:35], v[36:39], 0
	s_waitcnt lgkmcnt(0)
	v_mfma_f32_32x32x16_bf16 v[32:47], v[136:139], v[240:243], v[32:47]
	v_lshlrev_b32_e32 v137, 16, v133
	v_lshlrev_b32_e32 v136, 16, v132
	v_and_b32_e32 v133, 0xffff0000, v133
	v_and_b32_e32 v132, 0xffff0000, v132
	v_lshlrev_b32_e32 v139, 16, v135
	v_lshlrev_b32_e32 v138, 16, v134
	v_and_b32_e32 v135, 0xffff0000, v135
	v_and_b32_e32 v134, 0xffff0000, v134
	v_pk_mul_f32 v[132:133], v[156:157], v[132:133] op_sel_hi:[0,1]
	v_pk_mul_f32 v[134:135], v[156:157], v[134:135] op_sel_hi:[0,1]
	v_pk_mul_f32 v[136:137], v[156:157], v[136:137] op_sel_hi:[0,1]
	v_pk_mul_f32 v[138:139], v[156:157], v[138:139] op_sel_hi:[0,1]
	v_bfe_u32 v175, v135, 16, 1
	v_bfe_u32 v199, v134, 16, 1
	v_bfe_u32 v206, v133, 16, 1
	v_bfe_u32 v207, v132, 16, 1
	v_add3_u32 v132, v132, v207, s76
	v_add3_u32 v133, v133, v206, s76
	v_add3_u32 v134, v134, v199, s76
	v_add3_u32 v135, v135, v175, s76
	v_bfe_u32 v175, v136, 16, 1
	v_bfe_u32 v199, v137, 16, 1
	v_bfe_u32 v206, v138, 16, 1
	v_bfe_u32 v207, v139, 16, 1
	v_add3_u32 v139, v139, v207, s76
	v_add3_u32 v138, v138, v206, s76
	v_add3_u32 v137, v137, v199, s76
	v_add3_u32 v136, v136, v175, s76
	v_lshrrev_b32_e32 v136, 16, v136
	v_lshrrev_b32_e32 v137, 16, v137
	v_lshrrev_b32_e32 v138, 16, v138
	v_lshrrev_b32_e32 v139, 16, v139
	v_and_or_b32 v135, v135, s77, v139
	v_and_or_b32 v134, v134, s77, v138
	v_and_or_b32 v133, v133, s77, v137
	v_and_or_b32 v132, v132, s77, v136
	ds_read_b128 v[136:139], v197 offset:34880
	s_waitcnt lgkmcnt(0)
	v_mfma_f32_32x32x16_bf16 v[48:63], v[132:135], v[136:139], v[48:63]
	ds_read_b128 v[136:139], v197 offset:43584
	s_waitcnt lgkmcnt(0)
	v_mfma_f32_32x32x16_bf16 v[32:47], v[132:135], v[136:139], v[32:47]
	v_lshlrev_b32_e32 v133, 16, v129
	v_lshlrev_b32_e32 v132, 16, v128
	v_and_b32_e32 v129, 0xffff0000, v129
	v_and_b32_e32 v128, 0xffff0000, v128
	v_lshlrev_b32_e32 v135, 16, v131
	v_lshlrev_b32_e32 v134, 16, v130
	v_and_b32_e32 v131, 0xffff0000, v131
	v_and_b32_e32 v130, 0xffff0000, v130
	v_pk_mul_f32 v[128:129], v[156:157], v[128:129] op_sel_hi:[0,1]
	v_pk_mul_f32 v[130:131], v[156:157], v[130:131] op_sel_hi:[0,1]
	v_pk_mul_f32 v[132:133], v[156:157], v[132:133] op_sel_hi:[0,1]
	v_pk_mul_f32 v[134:135], v[156:157], v[134:135] op_sel_hi:[0,1]
	v_bfe_u32 v136, v131, 16, 1
	v_bfe_u32 v137, v130, 16, 1
	v_bfe_u32 v138, v129, 16, 1
	v_bfe_u32 v139, v128, 16, 1
	v_add3_u32 v128, v128, v139, s76
	v_add3_u32 v129, v129, v138, s76
	v_add3_u32 v130, v130, v137, s76
	v_add3_u32 v131, v131, v136, s76
	v_bfe_u32 v136, v132, 16, 1
	v_bfe_u32 v137, v133, 16, 1
	v_bfe_u32 v138, v134, 16, 1
	v_bfe_u32 v139, v135, 16, 1
	v_add3_u32 v135, v135, v139, s76
	v_add3_u32 v134, v134, v138, s76
	v_add3_u32 v133, v133, v137, s76
	v_add3_u32 v132, v132, v136, s76
	v_lshrrev_b32_e32 v132, 16, v132
	v_lshrrev_b32_e32 v133, 16, v133
	v_lshrrev_b32_e32 v134, 16, v134
	v_lshrrev_b32_e32 v135, 16, v135
	v_and_or_b32 v131, v131, s77, v135
	v_and_or_b32 v130, v130, s77, v134
	v_and_or_b32 v129, v129, s77, v133
	v_and_or_b32 v128, v128, s77, v132
	ds_read_b128 v[132:135], v197 offset:34912
	s_waitcnt lgkmcnt(0)
	v_mfma_f32_32x32x16_bf16 v[48:63], v[128:131], v[132:135], v[48:63]
	ds_read_b128 v[132:135], v197 offset:43616
	s_waitcnt lgkmcnt(0)
; DI u32 pack2(float a, float b) { return (u32)f2bf(a) | ((u32)f2bf(b) << 16); }
; DI float bflo(u32 v) { return __uint_as_float(v << 16); }
; DI float bfhi(u32 v) { return __uint_as_float(v & 0xffff0000u); }
; DI void ssd_item(const Params& p, int l, int it, char* smem) {
;     ...
;     {
;       const float eai = fea[w * 32 + l32];
; #pragma unroll
;       for (int ks = 0; ks < 8; ++ks) {
;         union { u32 u[4]; bf16x8 v; } t;
;         t.v = creg[ks];
; #pragma unroll
;         for (int q = 0; q < 4; ++q) t.u[q] = pack2(bflo(t.u[q]) * eai, bfhi(t.u[q]) * eai);
; #pragma unroll
;         for (int pb = 0; pb < 2; ++pb) {
;           const bf16x8 bb = *(const bf16x8*)&HL[(pb * 32 + l32) * 136 + ks * 16 + h * 8];
;           yd[pb] = __builtin_amdgcn_mfma_f32_32x32x16_bf16(t.v, bb, yd[pb], 0, 0, 0);
;         }
;       }
;     }
;     __syncthreads();
	v_mfma_f32_32x32x16_bf16 v[32:47], v[128:131], v[132:135], v[32:47]
	v_and_b32_e32 v131, 0xffff0000, v153
	v_and_b32_e32 v130, 0xffff0000, v152
	v_and_b32_e32 v135, 0xffff0000, v155
	v_and_b32_e32 v134, 0xffff0000, v154
	v_lshlrev_b32_e32 v129, 16, v153
	v_lshlrev_b32_e32 v128, 16, v152
	v_pk_mul_f32 v[130:131], v[156:157], v[130:131] op_sel_hi:[0,1]
	v_lshlrev_b32_e32 v133, 16, v155
	v_lshlrev_b32_e32 v132, 16, v154
	v_pk_mul_f32 v[134:135], v[156:157], v[134:135] op_sel_hi:[0,1]
	v_pk_mul_f32 v[128:129], v[156:157], v[128:129] op_sel_hi:[0,1]
	v_pk_mul_f32 v[132:133], v[156:157], v[132:133] op_sel_hi:[0,1]
	v_bfe_u32 v136, v135, 16, 1
	v_bfe_u32 v137, v134, 16, 1
	v_bfe_u32 v138, v131, 16, 1
	v_bfe_u32 v139, v130, 16, 1
	v_add3_u32 v139, v130, v139, s76
	v_add3_u32 v138, v131, v138, s76
	v_add3_u32 v130, v134, v137, s76
	v_add3_u32 v131, v135, v136, s76
	v_bfe_u32 v134, v128, 16, 1
	v_bfe_u32 v135, v129, 16, 1
	v_bfe_u32 v136, v132, 16, 1
	v_bfe_u32 v137, v133, 16, 1
	v_add3_u32 v133, v133, v137, s76
	v_add3_u32 v132, v132, v136, s76
	v_add3_u32 v129, v129, v135, s76
	v_add3_u32 v128, v128, v134, s76
	v_lshrrev_b32_e32 v128, 16, v128
	v_lshrrev_b32_e32 v129, 16, v129
	v_lshrrev_b32_e32 v132, 16, v132
	v_lshrrev_b32_e32 v133, 16, v133
	v_and_or_b32 v131, v131, s77, v133
	v_and_or_b32 v130, v130, s77, v132
	v_and_or_b32 v129, v138, s77, v129
	v_and_or_b32 v128, v139, s77, v128
	ds_read_b128 v[132:135], v197 offset:34944
	s_waitcnt lgkmcnt(0)
	v_mfma_f32_32x32x16_bf16 v[48:63], v[128:131], v[132:135], v[48:63]
	ds_read_b128 v[132:135], v197 offset:43648
	s_waitcnt lgkmcnt(0)
	v_mfma_f32_32x32x16_bf16 v[32:47], v[128:131], v[132:135], v[32:47]
	v_and_b32_e32 v131, 0xffff0000, v149
	v_and_b32_e32 v130, 0xffff0000, v148
	v_and_b32_e32 v135, 0xffff0000, v151
	v_and_b32_e32 v134, 0xffff0000, v150
	v_lshlrev_b32_e32 v129, 16, v149
	v_lshlrev_b32_e32 v128, 16, v148
	v_pk_mul_f32 v[130:131], v[156:157], v[130:131] op_sel_hi:[0,1]
	v_lshlrev_b32_e32 v133, 16, v151
	v_lshlrev_b32_e32 v132, 16, v150
	v_pk_mul_f32 v[134:135], v[156:157], v[134:135] op_sel_hi:[0,1]
	v_pk_mul_f32 v[128:129], v[156:157], v[128:129] op_sel_hi:[0,1]
	v_pk_mul_f32 v[132:133], v[156:157], v[132:133] op_sel_hi:[0,1]
	v_bfe_u32 v136, v135, 16, 1
	v_bfe_u32 v137, v134, 16, 1
	v_bfe_u32 v138, v131, 16, 1
	v_bfe_u32 v139, v130, 16, 1
	v_add3_u32 v139, v130, v139, s76
	v_add3_u32 v138, v131, v138, s76
	v_add3_u32 v130, v134, v137, s76
	v_add3_u32 v131, v135, v136, s76
	v_bfe_u32 v134, v128, 16, 1
	v_bfe_u32 v135, v129, 16, 1
	v_bfe_u32 v136, v132, 16, 1
	v_bfe_u32 v137, v133, 16, 1
	v_add3_u32 v133, v133, v137, s76
	v_add3_u32 v132, v132, v136, s76
	v_add3_u32 v129, v129, v135, s76
	v_add3_u32 v128, v128, v134, s76
	v_lshrrev_b32_e32 v128, 16, v128
	v_lshrrev_b32_e32 v129, 16, v129
	v_lshrrev_b32_e32 v132, 16, v132
	v_lshrrev_b32_e32 v133, 16, v133
	v_and_or_b32 v131, v131, s77, v133
	v_and_or_b32 v130, v130, s77, v132
	v_and_or_b32 v129, v138, s77, v129
	v_and_or_b32 v128, v139, s77, v128
	ds_read_b128 v[132:135], v197 offset:34976
	s_waitcnt lgkmcnt(0)
	v_mfma_f32_32x32x16_bf16 v[48:63], v[128:131], v[132:135], v[48:63]
	ds_read_b128 v[132:135], v197 offset:43680
	s_waitcnt lgkmcnt(0)
	v_mfma_f32_32x32x16_bf16 v[32:47], v[128:131], v[132:135], v[32:47]
	v_and_b32_e32 v131, 0xffff0000, v145
	v_and_b32_e32 v130, 0xffff0000, v144
	v_and_b32_e32 v135, 0xffff0000, v147
	v_and_b32_e32 v134, 0xffff0000, v146
	v_lshlrev_b32_e32 v129, 16, v145
	v_lshlrev_b32_e32 v128, 16, v144
	v_pk_mul_f32 v[130:131], v[156:157], v[130:131] op_sel_hi:[0,1]
	v_lshlrev_b32_e32 v133, 16, v147
	v_lshlrev_b32_e32 v132, 16, v146
	v_pk_mul_f32 v[134:135], v[156:157], v[134:135] op_sel_hi:[0,1]
	v_pk_mul_f32 v[128:129], v[156:157], v[128:129] op_sel_hi:[0,1]
	v_pk_mul_f32 v[132:133], v[156:157], v[132:133] op_sel_hi:[0,1]
	v_bfe_u32 v136, v135, 16, 1
	v_bfe_u32 v137, v134, 16, 1
	v_bfe_u32 v138, v131, 16, 1
	v_bfe_u32 v139, v130, 16, 1
	v_add3_u32 v139, v130, v139, s76
	v_add3_u32 v138, v131, v138, s76
	v_add3_u32 v130, v134, v137, s76
	v_add3_u32 v131, v135, v136, s76
	v_bfe_u32 v134, v128, 16, 1
	v_bfe_u32 v135, v129, 16, 1
	v_bfe_u32 v136, v132, 16, 1
	v_bfe_u32 v137, v133, 16, 1
	v_add3_u32 v133, v133, v137, s76
	v_add3_u32 v132, v132, v136, s76
	v_add3_u32 v129, v129, v135, s76
	v_add3_u32 v128, v128, v134, s76
	v_lshrrev_b32_e32 v128, 16, v128
	v_lshrrev_b32_e32 v129, 16, v129
	v_lshrrev_b32_e32 v132, 16, v132
	v_lshrrev_b32_e32 v133, 16, v133
	v_and_or_b32 v131, v131, s77, v133
	v_and_or_b32 v130, v130, s77, v132
	v_and_or_b32 v129, v138, s77, v129
	v_and_or_b32 v128, v139, s77, v128
	ds_read_b128 v[132:135], v197 offset:35008
	s_waitcnt lgkmcnt(0)
	v_mfma_f32_32x32x16_bf16 v[48:63], v[128:131], v[132:135], v[48:63]
	ds_read_b128 v[132:135], v197 offset:43712
	s_waitcnt lgkmcnt(0)
	v_mfma_f32_32x32x16_bf16 v[32:47], v[128:131], v[132:135], v[32:47]
	v_and_b32_e32 v131, 0xffff0000, v141
	v_and_b32_e32 v130, 0xffff0000, v140
	v_and_b32_e32 v135, 0xffff0000, v143
	v_and_b32_e32 v134, 0xffff0000, v142
	v_lshlrev_b32_e32 v129, 16, v141
	v_lshlrev_b32_e32 v128, 16, v140
	v_pk_mul_f32 v[130:131], v[156:157], v[130:131] op_sel_hi:[0,1]
	v_lshlrev_b32_e32 v133, 16, v143
	v_lshlrev_b32_e32 v132, 16, v142
	v_pk_mul_f32 v[134:135], v[156:157], v[134:135] op_sel_hi:[0,1]
	v_pk_mul_f32 v[128:129], v[156:157], v[128:129] op_sel_hi:[0,1]
	v_pk_mul_f32 v[132:133], v[156:157], v[132:133] op_sel_hi:[0,1]
	v_bfe_u32 v136, v135, 16, 1
	v_bfe_u32 v137, v134, 16, 1
	v_bfe_u32 v138, v131, 16, 1
	v_bfe_u32 v139, v130, 16, 1
	v_add3_u32 v139, v130, v139, s76
	v_add3_u32 v138, v131, v138, s76
	v_add3_u32 v130, v134, v137, s76
	v_add3_u32 v131, v135, v136, s76
	v_bfe_u32 v134, v128, 16, 1
	v_bfe_u32 v135, v129, 16, 1
	v_bfe_u32 v136, v132, 16, 1
	v_bfe_u32 v137, v133, 16, 1
	v_add3_u32 v133, v133, v137, s76
	v_add3_u32 v132, v132, v136, s76
	v_add3_u32 v129, v129, v135, s76
	v_add3_u32 v128, v128, v134, s76
	v_lshrrev_b32_e32 v128, 16, v128
	v_lshrrev_b32_e32 v129, 16, v129
	v_lshrrev_b32_e32 v132, 16, v132
	v_lshrrev_b32_e32 v133, 16, v133
	v_and_or_b32 v131, v131, s77, v133
	v_and_or_b32 v130, v130, s77, v132
	v_and_or_b32 v129, v138, s77, v129
	v_and_or_b32 v128, v139, s77, v128
	ds_read_b128 v[132:135], v197 offset:35040
	v_mov_b32_e32 v142, v236
	s_waitcnt lgkmcnt(0)
	v_mfma_f32_32x32x16_bf16 v[48:63], v[128:131], v[132:135], v[48:63]
	ds_read_b128 v[132:135], v197 offset:43744
	s_waitcnt lgkmcnt(0)
	s_barrier
; DI u16 f2bf(float x) { u32 u = __float_as_uint(x); u += 0x7fffu + ((u >> 16) & 1u); return (u16)(u >> 16); }
; DI void ssd_item(const Params& p, int l, int it, char* smem) {
;     ...
; #pragma unroll
;     for (int jb = 0; jb < 4; ++jb) {
;       const int j = jb * 32 + l32v;
;       const float aj = fa[j], dtj = fdt[j];
; #pragma unroll
;       for (int r = 0; r < 16; ++r) {
;         const int i = w * 32 + (r & 3) + 8 * (r >> 2) + 4 * hv_;
;         const float ai = fa[i];
;         const bool valid = dir ? (j >= i) : (j <= i);
;         const float v = valid ? acc[jb][r] * __expf(ai - aj) * dtj : 0.f;
;         BG[i * 136 + j] = f2bf(v);
;       }
	v_cndmask_b32_e64 v233, -1, 1, s[36:37]
	v_lshlrev_b32_e32 v232, 3, v233
	v_lshlrev_b32_e32 v230, 1, v233
	v_add_u32_e32 v229, v230, v233
	v_mfma_f32_32x32x16_bf16 v[32:47], v[128:131], v[132:135], v[32:47]
	v_mov_b32_e32 v128, v235
	v_mov_b32_e32 v135, 0
	v_lshlrev_b32_e32 v134, 2, v142
	v_lshl_add_u32 v136, v128, 2, 0
	v_add_u32_e32 v130, v134, v237
	ds_read2st64_b32 v[132:133], v136 offset0:204 offset1:206
	v_sub_u32_e32 v228, v128, v130
	v_mul_i32_i24_e32 v228, v228, v233
	v_mad_i32_i24 v227, v232, 0, v228
	s_nop 0
	v_cmp_ge_i32_e32 vcc, 0, v227
	v_lshl_add_u32 v129, v130, 2, 0
	ds_read_b32 v208, v129 offset:52224
	ds_read_b32 v209, v129 offset:52228
	ds_read_b32 v210, v129 offset:52232
	ds_read_b32 v211, v129 offset:52236
	ds_read_b32 v212, v129 offset:52256
	ds_read_b32 v213, v129 offset:52260
	ds_read_b32 v219, v129 offset:52264
	ds_read_b32 v220, v129 offset:52268
	ds_read_b32 v221, v129 offset:52288
	ds_read_b32 v222, v129 offset:52292
	ds_read_b32 v223, v129 offset:52296
	ds_read_b32 v224, v129 offset:52300
	ds_read_b32 v225, v129 offset:52320
	ds_read_b32 v226, v129 offset:52324
	ds_read_b32 v202, v129 offset:52328
	ds_read_b32 v203, v129 offset:52332
	v_mov_b32_e32 v131, 0
	s_waitcnt lgkmcnt(0)
	s_and_saveexec_b64 s[0:1], vcc
	s_cbranch_execz .LBB0_998
	v_sub_f32_e32 v131, v208, v132
	v_mul_f32_e32 v131, 0x3fb8aa3b, v131
	v_exp_f32_e32 v131, v131
	s_nop 0
	v_mul_f32_e32 v112, v112, v131
	v_mul_f32_e32 v131, v133, v112
.LBB0_998:
	s_or_b64 exec, exec, s[0:1]
	v_lshlrev_b32_e32 v143, 1, v128
	v_bfe_u32 v137, v131, 16, 1
	v_sub_u32_e32 v112, v136, v143
	v_add3_u32 v131, v131, v137, s76
	v_mul_lo_u32 v137, v130, s52
	v_add_u32_e32 v138, v112, v137
	ds_write_b16_d16_hi v138, v131
	v_or_b32_e32 v131, 1, v237
	v_add_u32_e32 v131, v134, v131
	v_cmp_le_i32_e32 vcc, v227, v233
	s_and_saveexec_b64 s[0:1], vcc
	s_cbranch_execz .LBB0_1000
	v_sub_f32_e32 v135, v209, v132
	v_mul_f32_e32 v135, 0x3fb8aa3b, v135
	v_exp_f32_e32 v135, v135
	s_nop 0
	v_mul_f32_e32 v113, v113, v135
	v_mul_f32_e32 v135, v133, v113
.LBB0_1000:
	s_or_b64 exec, exec, s[0:1]
	v_bfe_u32 v113, v135, 16, 1
	v_add3_u32 v113, v135, v113, s76
	v_mul_lo_u32 v135, v131, s52
	v_add_u32_e32 v140, v112, v135
	ds_write_b16_d16_hi v140, v113
	v_or_b32_e32 v113, 2, v237
	v_add_u32_e32 v139, v134, v113
	v_cmp_le_i32_e32 vcc, v227, v230
	v_mov_b32_e32 v113, 0
	v_mov_b32_e32 v135, 0
	s_and_saveexec_b64 s[0:1], vcc
	s_cbranch_execz .LBB0_1002
	v_sub_f32_e32 v135, v210, v132
	v_mul_f32_e32 v135, 0x3fb8aa3b, v135
	v_exp_f32_e32 v135, v135
	s_nop 0
	v_mul_f32_e32 v114, v114, v135
	v_mul_f32_e32 v135, v133, v114
.LBB0_1002:
	s_or_b64 exec, exec, s[0:1]
	v_bfe_u32 v114, v135, 16, 1
	v_add3_u32 v114, v135, v114, s76
	v_mul_lo_u32 v135, v139, s52
	v_add_u32_e32 v144, v112, v135
	ds_write_b16_d16_hi v144, v114
	v_or_b32_e32 v114, 3, v237
	v_add_u32_e32 v141, v134, v114
	v_cmp_le_i32_e32 vcc, v227, v229
	s_and_saveexec_b64 s[0:1], vcc
	s_cbranch_execz .LBB0_1004
	v_sub_f32_e32 v113, v211, v132
	v_mul_f32_e32 v113, 0x3fb8aa3b, v113
	v_exp_f32_e32 v113, v113
	s_nop 0
	v_mul_f32_e32 v113, v115, v113
	v_mul_f32_e32 v113, v133, v113
.LBB0_1004:
	s_or_b64 exec, exec, s[0:1]
	v_bfe_u32 v114, v113, 16, 1
	v_add3_u32 v113, v113, v114, s76
	v_mul_lo_u32 v114, v141, s52
	v_add_u32_e32 v146, v112, v114
	ds_write_b16_d16_hi v146, v113
	v_or_b32_e32 v113, 8, v237
	v_add_u32_e32 v145, v134, v113
	v_mad_i32_i24 v227, v232, -1, v228
	v_cmp_ge_i32_e32 vcc, 0, v227
	v_mov_b32_e32 v113, 0
	v_mov_b32_e32 v114, 0
	s_and_saveexec_b64 s[0:1], vcc
	s_cbranch_execz .LBB0_1006
	v_sub_f32_e32 v114, v212, v132
	v_mul_f32_e32 v114, 0x3fb8aa3b, v114
	v_exp_f32_e32 v114, v114
	s_nop 0
	v_mul_f32_e32 v114, v116, v114
	v_mul_f32_e32 v114, v133, v114
.LBB0_1006:
	s_or_b64 exec, exec, s[0:1]
	v_bfe_u32 v115, v114, 16, 1
	v_add3_u32 v114, v114, v115, s76
	v_mul_lo_u32 v115, v145, s52
	v_add_u32_e32 v148, v112, v115
	ds_write_b16_d16_hi v148, v114
	v_or_b32_e32 v114, 9, v237
	v_add_u32_e32 v147, v134, v114
	v_cmp_le_i32_e32 vcc, v227, v233
	s_and_saveexec_b64 s[0:1], vcc
	s_cbranch_execz .LBB0_1008
	v_sub_f32_e32 v113, v213, v132
	v_mul_f32_e32 v113, 0x3fb8aa3b, v113
	v_exp_f32_e32 v113, v113
	s_nop 0
	v_mul_f32_e32 v113, v117, v113
	v_mul_f32_e32 v113, v133, v113
.LBB0_1008:
	s_or_b64 exec, exec, s[0:1]
	v_bfe_u32 v114, v113, 16, 1
	v_add3_u32 v113, v113, v114, s76
	v_mul_lo_u32 v114, v147, s52
	v_add_u32_e32 v150, v112, v114
	ds_write_b16_d16_hi v150, v113
	v_or_b32_e32 v113, 10, v237
	v_add_u32_e32 v149, v134, v113
	v_cmp_le_i32_e32 vcc, v227, v230
	v_mov_b32_e32 v113, 0
	v_mov_b32_e32 v114, 0
	s_and_saveexec_b64 s[0:1], vcc
	s_cbranch_execz .LBB0_1010
	v_sub_f32_e32 v114, v219, v132
	v_mul_f32_e32 v114, 0x3fb8aa3b, v114
	v_exp_f32_e32 v114, v114
	s_nop 0
	v_mul_f32_e32 v114, v118, v114
	v_mul_f32_e32 v114, v133, v114
.LBB0_1010:
	s_or_b64 exec, exec, s[0:1]
	v_bfe_u32 v115, v114, 16, 1
	v_add3_u32 v114, v114, v115, s76
	v_mul_lo_u32 v115, v149, s52
	v_add_u32_e32 v152, v112, v115
	ds_write_b16_d16_hi v152, v114
	v_or_b32_e32 v114, 11, v237
	v_add_u32_e32 v151, v134, v114
	v_cmp_le_i32_e32 vcc, v227, v229
	s_and_saveexec_b64 s[0:1], vcc
	s_cbranch_execz .LBB0_1012
	v_sub_f32_e32 v113, v220, v132
	v_mul_f32_e32 v113, 0x3fb8aa3b, v113
	v_exp_f32_e32 v113, v113
	s_nop 0
	v_mul_f32_e32 v113, v119, v113
	v_mul_f32_e32 v113, v133, v113
.LBB0_1012:
	s_or_b64 exec, exec, s[0:1]
	v_bfe_u32 v114, v113, 16, 1
	v_add3_u32 v113, v113, v114, s76
	v_mul_lo_u32 v114, v151, s52
	v_add_u32_e32 v154, v112, v114
	ds_write_b16_d16_hi v154, v113
	v_or_b32_e32 v113, 16, v237
	v_add_u32_e32 v153, v134, v113
	v_mad_i32_i24 v227, v232, -2, v228
	v_cmp_ge_i32_e32 vcc, 0, v227
	v_mov_b32_e32 v113, 0
	v_mov_b32_e32 v114, 0
	s_and_saveexec_b64 s[0:1], vcc
	s_cbranch_execz .LBB0_1014
	v_sub_f32_e32 v114, v221, v132
	v_mul_f32_e32 v114, 0x3fb8aa3b, v114
	v_exp_f32_e32 v114, v114
	s_nop 0
	v_mul_f32_e32 v114, v120, v114
	v_mul_f32_e32 v114, v133, v114
; DI u16 f2bf(float x) { u32 u = __float_as_uint(x); u += 0x7fffu + ((u >> 16) & 1u); return (u16)(u >> 16); }
; DI void ssd_item(const Params& p, int l, int it, char* smem) {
;     ...
; #pragma unroll
;     for (int jb = 0; jb < 4; ++jb) {
;       const int j = jb * 32 + l32v;
;       const float aj = fa[j], dtj = fdt[j];
; #pragma unroll
;       for (int r = 0; r < 16; ++r) {
;         const int i = w * 32 + (r & 3) + 8 * (r >> 2) + 4 * hv_;
;         const float ai = fa[i];
;         const bool valid = dir ? (j >= i) : (j <= i);
;         const float v = valid ? acc[jb][r] * __expf(ai - aj) * dtj : 0.f;
;         BG[i * 136 + j] = f2bf(v);
;       }
.LBB0_1014:
	s_or_b64 exec, exec, s[0:1]
	v_bfe_u32 v115, v114, 16, 1
	v_add3_u32 v114, v114, v115, s76
	v_mul_lo_u32 v115, v153, s52
	v_add_u32_e32 v156, v112, v115
	ds_write_b16_d16_hi v156, v114
	v_or_b32_e32 v114, 17, v237
	v_add_u32_e32 v155, v134, v114
	v_cmp_le_i32_e32 vcc, v227, v233
	s_and_saveexec_b64 s[0:1], vcc
	s_cbranch_execz .LBB0_1016
	v_sub_f32_e32 v113, v222, v132
	v_mul_f32_e32 v113, 0x3fb8aa3b, v113
	v_exp_f32_e32 v113, v113
	s_nop 0
	v_mul_f32_e32 v113, v121, v113
	v_mul_f32_e32 v113, v133, v113
.LBB0_1016:
	s_or_b64 exec, exec, s[0:1]
	v_bfe_u32 v114, v113, 16, 1
	v_add3_u32 v113, v113, v114, s76
	v_mul_lo_u32 v114, v155, s52
	v_add_u32_e32 v175, v134, v165
	v_add_u32_e32 v199, v112, v114
	ds_write_b16_d16_hi v199, v113
	s_nop 0
	v_cmp_le_i32_e32 vcc, v227, v230
	v_mov_b32_e32 v113, 0
	v_mov_b32_e32 v114, 0
	s_and_saveexec_b64 s[0:1], vcc
	s_cbranch_execz .LBB0_1018
	v_sub_f32_e32 v114, v223, v132
	v_mul_f32_e32 v114, 0x3fb8aa3b, v114
	v_exp_f32_e32 v114, v114
	s_nop 0
	v_mul_f32_e32 v114, v122, v114
	v_mul_f32_e32 v114, v133, v114
.LBB0_1018:
	s_or_b64 exec, exec, s[0:1]
	v_bfe_u32 v115, v114, 16, 1
	v_add3_u32 v114, v114, v115, s76
	v_mul_lo_u32 v115, v175, s52
	v_add_u32_e32 v240, v134, v169
	v_add_u32_e32 v241, v112, v115
	ds_write_b16_d16_hi v241, v114
	s_nop 0
	v_cmp_le_i32_e32 vcc, v227, v229
	s_and_saveexec_b64 s[0:1], vcc
	s_cbranch_execz .LBB0_1020
	v_sub_f32_e32 v113, v224, v132
	v_mul_f32_e32 v113, 0x3fb8aa3b, v113
	v_exp_f32_e32 v113, v113
	s_nop 0
	v_mul_f32_e32 v113, v123, v113
	v_mul_f32_e32 v113, v133, v113
.LBB0_1020:
	s_or_b64 exec, exec, s[0:1]
	v_bfe_u32 v114, v113, 16, 1
	v_add3_u32 v113, v113, v114, s76
	v_mul_lo_u32 v114, v240, s52
	v_add_u32_e32 v242, v134, v177
	v_add_u32_e32 v243, v112, v114
	v_mad_i32_i24 v227, v232, -3, v228
	ds_write_b16_d16_hi v243, v113
	s_nop 0
	v_cmp_ge_i32_e32 vcc, 0, v227
	v_mov_b32_e32 v113, 0
	v_mov_b32_e32 v114, 0
	s_and_saveexec_b64 s[0:1], vcc
	s_cbranch_execz .LBB0_1022
	v_sub_f32_e32 v114, v225, v132
	v_mul_f32_e32 v114, 0x3fb8aa3b, v114
	v_exp_f32_e32 v114, v114
	s_nop 0
	v_mul_f32_e32 v114, v124, v114
	v_mul_f32_e32 v114, v133, v114
.LBB0_1022:
	s_or_b64 exec, exec, s[0:1]
	v_bfe_u32 v115, v114, 16, 1
	v_add3_u32 v114, v114, v115, s76
	v_mul_lo_u32 v115, v242, s52
	v_add_u32_e32 v244, v134, v181
	v_add_u32_e32 v245, v112, v115
	ds_write_b16_d16_hi v245, v114
	s_nop 0
	v_cmp_le_i32_e32 vcc, v227, v233
	s_and_saveexec_b64 s[0:1], vcc
	s_cbranch_execz .LBB0_1024
	v_sub_f32_e32 v113, v226, v132
	v_mul_f32_e32 v113, 0x3fb8aa3b, v113
	v_exp_f32_e32 v113, v113
	s_nop 0
	v_mul_f32_e32 v113, v125, v113
	v_mul_f32_e32 v113, v133, v113
.LBB0_1024:
	s_or_b64 exec, exec, s[0:1]
	v_bfe_u32 v114, v113, 16, 1
	v_add3_u32 v113, v113, v114, s76
	v_mul_lo_u32 v114, v244, s52
	v_add_u32_e32 v246, v134, v185
	v_add_u32_e32 v247, v112, v114
	ds_write_b16_d16_hi v247, v113
	s_nop 0
	v_cmp_le_i32_e32 vcc, v227, v230
	v_mov_b32_e32 v113, 0
	v_mov_b32_e32 v114, 0
	s_and_saveexec_b64 s[0:1], vcc
	s_cbranch_execz .LBB0_1026
	v_sub_f32_e32 v114, v202, v132
	v_mul_f32_e32 v114, 0x3fb8aa3b, v114
	v_exp_f32_e32 v114, v114
	s_nop 0
	v_mul_f32_e32 v114, v126, v114
	v_mul_f32_e32 v114, v133, v114
.LBB0_1026:
	s_or_b64 exec, exec, s[0:1]
	v_bfe_u32 v115, v114, 16, 1
	v_add3_u32 v114, v114, v115, s76
	v_mul_lo_u32 v115, v246, s52
	v_add_u32_e32 v248, v134, v189
	v_add_u32_e32 v249, v112, v115
	ds_write_b16_d16_hi v249, v114
	s_nop 0
	v_cmp_le_i32_e32 vcc, v227, v229
	s_and_saveexec_b64 s[0:1], vcc
	s_cbranch_execz .LBB0_1028
	v_sub_f32_e32 v113, v203, v132
	v_mul_f32_e32 v113, 0x3fb8aa3b, v113
	v_exp_f32_e32 v113, v113
	s_nop 0
	v_mul_f32_e32 v113, v127, v113
	v_mul_f32_e32 v113, v133, v113
.LBB0_1028:
	s_or_b64 exec, exec, s[0:1]
	v_bfe_u32 v114, v113, 16, 1
	v_add3_u32 v113, v113, v114, s76
	v_mul_lo_u32 v114, v248, s52
	v_add_u32_e32 v250, v112, v114
	ds_write_b16_d16_hi v250, v113
	v_add_u32_e32 v114, 32, v128
	v_add_u32_e32 v251, 0x80, v136
	v_sub_u32_e32 v228, v114, v130
	v_mul_i32_i24_e32 v228, v228, v233
	v_mad_i32_i24 v227, v232, 0, v228
	ds_read2st64_b32 v[112:113], v251 offset0:204 offset1:206
	s_nop 0
	v_cmp_ge_i32_e32 vcc, 0, v227
	v_mov_b32_e32 v115, 0
	v_mov_b32_e32 v116, 0
	s_waitcnt lgkmcnt(0)
	s_and_saveexec_b64 s[0:1], vcc
	s_cbranch_execz .LBB0_1030
	v_sub_f32_e32 v116, v208, v112
	v_mul_f32_e32 v116, 0x3fb8aa3b, v116
	v_exp_f32_e32 v116, v116
	s_nop 0
	v_mul_f32_e32 v96, v96, v116
	v_mul_f32_e32 v116, v113, v96
.LBB0_1030:
	s_or_b64 exec, exec, s[0:1]
	v_bfe_u32 v96, v116, 16, 1
	v_add3_u32 v96, v116, v96, s76
	ds_write_b16_d16_hi v138, v96 offset:64
	s_nop 0
	v_cmp_le_i32_e32 vcc, v227, v233
	s_and_saveexec_b64 s[0:1], vcc
	s_cbranch_execz .LBB0_1032
	v_sub_f32_e32 v96, v209, v112
	v_mul_f32_e32 v96, 0x3fb8aa3b, v96
	v_exp_f32_e32 v96, v96
	s_nop 0
	v_mul_f32_e32 v96, v97, v96
	v_mul_f32_e32 v115, v113, v96
.LBB0_1032:
	s_or_b64 exec, exec, s[0:1]
	v_bfe_u32 v96, v115, 16, 1
	v_add3_u32 v96, v115, v96, s76
	ds_write_b16_d16_hi v140, v96 offset:64
	s_nop 0
	v_cmp_le_i32_e32 vcc, v227, v230
	v_mov_b32_e32 v96, 0
	v_mov_b32_e32 v97, 0
	s_and_saveexec_b64 s[0:1], vcc
	s_cbranch_execz .LBB0_1034
	v_sub_f32_e32 v97, v210, v112
	v_mul_f32_e32 v97, 0x3fb8aa3b, v97
	v_exp_f32_e32 v97, v97
	s_nop 0
	v_mul_f32_e32 v97, v98, v97
	v_mul_f32_e32 v97, v113, v97
.LBB0_1034:
	s_or_b64 exec, exec, s[0:1]
	v_bfe_u32 v98, v97, 16, 1
	v_add3_u32 v97, v97, v98, s76
	ds_write_b16_d16_hi v144, v97 offset:64
	s_nop 0
	v_cmp_le_i32_e32 vcc, v227, v229
	s_and_saveexec_b64 s[0:1], vcc
	s_cbranch_execz .LBB0_1036
	v_sub_f32_e32 v96, v211, v112
	v_mul_f32_e32 v96, 0x3fb8aa3b, v96
	v_exp_f32_e32 v96, v96
	s_nop 0
	v_mul_f32_e32 v96, v99, v96
	v_mul_f32_e32 v96, v113, v96
; DI u16 f2bf(float x) { u32 u = __float_as_uint(x); u += 0x7fffu + ((u >> 16) & 1u); return (u16)(u >> 16); }
; DI void ssd_item(const Params& p, int l, int it, char* smem) {
;     ...
; #pragma unroll
;     for (int jb = 0; jb < 4; ++jb) {
;       const int j = jb * 32 + l32v;
;       const float aj = fa[j], dtj = fdt[j];
; #pragma unroll
;       for (int r = 0; r < 16; ++r) {
;         const int i = w * 32 + (r & 3) + 8 * (r >> 2) + 4 * hv_;
;         const float ai = fa[i];
;         const bool valid = dir ? (j >= i) : (j <= i);
;         const float v = valid ? acc[jb][r] * __expf(ai - aj) * dtj : 0.f;
;         BG[i * 136 + j] = f2bf(v);
;       }
.LBB0_1036:
	s_or_b64 exec, exec, s[0:1]
	v_bfe_u32 v97, v96, 16, 1
	v_add3_u32 v96, v96, v97, s76
	v_mad_i32_i24 v227, v232, -1, v228
	ds_write_b16_d16_hi v146, v96 offset:64
	s_nop 0
	v_cmp_ge_i32_e32 vcc, 0, v227
	v_mov_b32_e32 v96, 0
	v_mov_b32_e32 v97, 0
	s_and_saveexec_b64 s[0:1], vcc
	s_cbranch_execz .LBB0_1038
	v_sub_f32_e32 v97, v212, v112
	v_mul_f32_e32 v97, 0x3fb8aa3b, v97
	v_exp_f32_e32 v97, v97
	s_nop 0
	v_mul_f32_e32 v97, v100, v97
	v_mul_f32_e32 v97, v113, v97
.LBB0_1038:
	s_or_b64 exec, exec, s[0:1]
	v_bfe_u32 v98, v97, 16, 1
	v_add3_u32 v97, v97, v98, s76
	ds_write_b16_d16_hi v148, v97 offset:64
	s_nop 0
	v_cmp_le_i32_e32 vcc, v227, v233
	s_and_saveexec_b64 s[0:1], vcc
	s_cbranch_execz .LBB0_1040
	v_sub_f32_e32 v96, v213, v112
	v_mul_f32_e32 v96, 0x3fb8aa3b, v96
	v_exp_f32_e32 v96, v96
	s_nop 0
	v_mul_f32_e32 v96, v101, v96
	v_mul_f32_e32 v96, v113, v96
.LBB0_1040:
	s_or_b64 exec, exec, s[0:1]
	v_bfe_u32 v97, v96, 16, 1
	v_add3_u32 v96, v96, v97, s76
	ds_write_b16_d16_hi v150, v96 offset:64
	s_nop 0
	v_cmp_le_i32_e32 vcc, v227, v230
	v_mov_b32_e32 v96, 0
	v_mov_b32_e32 v97, 0
	s_and_saveexec_b64 s[0:1], vcc
	s_cbranch_execz .LBB0_1042
	v_sub_f32_e32 v97, v219, v112
	v_mul_f32_e32 v97, 0x3fb8aa3b, v97
	v_exp_f32_e32 v97, v97
	s_nop 0
	v_mul_f32_e32 v97, v102, v97
	v_mul_f32_e32 v97, v113, v97
.LBB0_1042:
	s_or_b64 exec, exec, s[0:1]
	v_bfe_u32 v98, v97, 16, 1
	v_add3_u32 v97, v97, v98, s76
	ds_write_b16_d16_hi v152, v97 offset:64
	s_nop 0
	v_cmp_le_i32_e32 vcc, v227, v229
	s_and_saveexec_b64 s[0:1], vcc
	s_cbranch_execz .LBB0_1044
	v_sub_f32_e32 v96, v220, v112
	v_mul_f32_e32 v96, 0x3fb8aa3b, v96
	v_exp_f32_e32 v96, v96
	s_nop 0
	v_mul_f32_e32 v96, v103, v96
	v_mul_f32_e32 v96, v113, v96
.LBB0_1044:
	s_or_b64 exec, exec, s[0:1]
	v_bfe_u32 v97, v96, 16, 1
	v_add3_u32 v96, v96, v97, s76
	v_mad_i32_i24 v227, v232, -2, v228
	ds_write_b16_d16_hi v154, v96 offset:64
	s_nop 0
	v_cmp_ge_i32_e32 vcc, 0, v227
	v_mov_b32_e32 v96, 0
	v_mov_b32_e32 v97, 0
	s_and_saveexec_b64 s[0:1], vcc
	s_cbranch_execz .LBB0_1046
	v_sub_f32_e32 v97, v221, v112
	v_mul_f32_e32 v97, 0x3fb8aa3b, v97
	v_exp_f32_e32 v97, v97
	s_nop 0
	v_mul_f32_e32 v97, v104, v97
	v_mul_f32_e32 v97, v113, v97
.LBB0_1046:
	s_or_b64 exec, exec, s[0:1]
	v_bfe_u32 v98, v97, 16, 1
	v_add3_u32 v97, v97, v98, s76
	ds_write_b16_d16_hi v156, v97 offset:64
	s_nop 0
	v_cmp_le_i32_e32 vcc, v227, v233
	s_and_saveexec_b64 s[0:1], vcc
	s_cbranch_execz .LBB0_1048
	v_sub_f32_e32 v96, v222, v112
	v_mul_f32_e32 v96, 0x3fb8aa3b, v96
	v_exp_f32_e32 v96, v96
	s_nop 0
	v_mul_f32_e32 v96, v105, v96
	v_mul_f32_e32 v96, v113, v96
.LBB0_1048:
	s_or_b64 exec, exec, s[0:1]
	v_bfe_u32 v97, v96, 16, 1
	v_add3_u32 v96, v96, v97, s76
	ds_write_b16_d16_hi v199, v96 offset:64
	s_nop 0
	v_cmp_le_i32_e32 vcc, v227, v230
	v_mov_b32_e32 v96, 0
	v_mov_b32_e32 v97, 0
	s_and_saveexec_b64 s[0:1], vcc
	s_cbranch_execz .LBB0_1050
	v_sub_f32_e32 v97, v223, v112
	v_mul_f32_e32 v97, 0x3fb8aa3b, v97
	v_exp_f32_e32 v97, v97
	s_nop 0
	v_mul_f32_e32 v97, v106, v97
	v_mul_f32_e32 v97, v113, v97
.LBB0_1050:
	s_or_b64 exec, exec, s[0:1]
	v_bfe_u32 v98, v97, 16, 1
	v_add3_u32 v97, v97, v98, s76
	ds_write_b16_d16_hi v241, v97 offset:64
	s_nop 0
	v_cmp_le_i32_e32 vcc, v227, v229
	s_and_saveexec_b64 s[0:1], vcc
	s_cbranch_execz .LBB0_1052
	v_sub_f32_e32 v96, v224, v112
	v_mul_f32_e32 v96, 0x3fb8aa3b, v96
	v_exp_f32_e32 v96, v96
	s_nop 0
	v_mul_f32_e32 v96, v107, v96
	v_mul_f32_e32 v96, v113, v96
.LBB0_1052:
	s_or_b64 exec, exec, s[0:1]
	v_bfe_u32 v97, v96, 16, 1
	v_add3_u32 v96, v96, v97, s76
	v_mad_i32_i24 v227, v232, -3, v228
	ds_write_b16_d16_hi v243, v96 offset:64
	s_nop 0
	v_cmp_ge_i32_e32 vcc, 0, v227
	v_mov_b32_e32 v96, 0
	v_mov_b32_e32 v97, 0
	s_and_saveexec_b64 s[0:1], vcc
	s_cbranch_execz .LBB0_1054
	v_sub_f32_e32 v97, v225, v112
	v_mul_f32_e32 v97, 0x3fb8aa3b, v97
	v_exp_f32_e32 v97, v97
	s_nop 0
	v_mul_f32_e32 v97, v108, v97
	v_mul_f32_e32 v97, v113, v97
.LBB0_1054:
	s_or_b64 exec, exec, s[0:1]
	v_bfe_u32 v98, v97, 16, 1
	v_add3_u32 v97, v97, v98, s76
	ds_write_b16_d16_hi v245, v97 offset:64
	s_nop 0
	v_cmp_le_i32_e32 vcc, v227, v233
	s_and_saveexec_b64 s[0:1], vcc
	s_cbranch_execz .LBB0_1056
	v_sub_f32_e32 v96, v226, v112
	v_mul_f32_e32 v96, 0x3fb8aa3b, v96
	v_exp_f32_e32 v96, v96
	s_nop 0
	v_mul_f32_e32 v96, v109, v96
	v_mul_f32_e32 v96, v113, v96
.LBB0_1056:
	s_or_b64 exec, exec, s[0:1]
	v_bfe_u32 v97, v96, 16, 1
	v_add3_u32 v96, v96, v97, s76
	ds_write_b16_d16_hi v247, v96 offset:64
	s_nop 0
	v_cmp_le_i32_e32 vcc, v227, v230
	v_mov_b32_e32 v96, 0
	v_mov_b32_e32 v97, 0
	s_and_saveexec_b64 s[0:1], vcc
	s_cbranch_execz .LBB0_1058
	v_sub_f32_e32 v97, v202, v112
	v_mul_f32_e32 v97, 0x3fb8aa3b, v97
	v_exp_f32_e32 v97, v97
	s_nop 0
	v_mul_f32_e32 v97, v110, v97
	v_mul_f32_e32 v97, v113, v97
.LBB0_1058:
	s_or_b64 exec, exec, s[0:1]
	v_bfe_u32 v98, v97, 16, 1
	v_add3_u32 v97, v97, v98, s76
	ds_write_b16_d16_hi v249, v97 offset:64
	s_nop 0
	v_cmp_le_i32_e32 vcc, v227, v229
	s_and_saveexec_b64 s[0:1], vcc
	s_cbranch_execz .LBB0_1060
	v_sub_f32_e32 v96, v203, v112
	v_mul_f32_e32 v96, 0x3fb8aa3b, v96
	v_exp_f32_e32 v96, v96
	s_nop 0
	v_mul_f32_e32 v96, v111, v96
	v_mul_f32_e32 v96, v113, v96
; DI u16 f2bf(float x) { u32 u = __float_as_uint(x); u += 0x7fffu + ((u >> 16) & 1u); return (u16)(u >> 16); }
; DI void ssd_item(const Params& p, int l, int it, char* smem) {
;     ...
; #pragma unroll
;     for (int jb = 0; jb < 4; ++jb) {
;       const int j = jb * 32 + l32v;
;       const float aj = fa[j], dtj = fdt[j];
; #pragma unroll
;       for (int r = 0; r < 16; ++r) {
;         const int i = w * 32 + (r & 3) + 8 * (r >> 2) + 4 * hv_;
;         const float ai = fa[i];
;         const bool valid = dir ? (j >= i) : (j <= i);
;         const float v = valid ? acc[jb][r] * __expf(ai - aj) * dtj : 0.f;
;         BG[i * 136 + j] = f2bf(v);
;       }
;       __builtin_amdgcn_sched_barrier(0);
;       if (jb == 1) {
; #pragma unroll
;         for (int ks = 0; ks < 8; ++ks) xf[0][ks] = *(const bf16x8*)(xt + ks * 16);
;         __builtin_amdgcn_sched_barrier(0);
;       }
.LBB0_1060:
	s_or_b64 exec, exec, s[0:1]
	v_add_u32_e32 v97, s84, v128
	v_mov_b64_e32 v[98:99], s[4:5]
	v_mad_i64_i32 v[98:99], s[0:1], v97, s9, v[98:99]
	s_waitcnt lgkmcnt(14)
	v_lshlrev_b32_e32 v132, 3, v142
	v_lshl_add_u64 v[98:99], s[86:87], 1, v[98:99]
	v_ashrrev_i32_e32 v133, 31, v132
	v_bfe_u32 v97, v96, 16, 1
	v_lshl_add_u64 v[134:135], v[132:133], 1, v[98:99]
	v_add3_u32 v96, v96, v97, s76
	ds_write_b16_d16_hi v250, v96 offset:64
	global_load_dwordx4 v[124:127], v[134:135], off
	global_load_dwordx4 v[120:123], v[134:135], off offset:32
	global_load_dwordx4 v[116:119], v[134:135], off offset:64
	global_load_dwordx4 v[112:115], v[134:135], off offset:96
	global_load_dwordx4 v[108:111], v[134:135], off offset:128
	global_load_dwordx4 v[104:107], v[134:135], off offset:160
	global_load_dwordx4 v[100:103], v[134:135], off offset:192
	global_load_dwordx4 v[96:99], v[134:135], off offset:224
	v_add_u32_e32 v252, 64, v128
	v_sub_u32_e32 v228, v252, v130
	v_mul_i32_i24_e32 v228, v228, v233
	v_mad_i32_i24 v227, v232, 0, v228
	ds_read2st64_b32 v[136:137], v136 offset0:205 offset1:207
	v_mov_b32_e32 v214, 0
	v_cmp_ge_i32_e32 vcc, 0, v227
	v_mov_b32_e32 v206, 0
	s_waitcnt lgkmcnt(0)
	s_and_saveexec_b64 s[0:1], vcc
	s_cbranch_execz .LBB0_1062
	v_sub_f32_e32 v206, v208, v136
	v_mul_f32_e32 v206, 0x3fb8aa3b, v206
	v_exp_f32_e32 v206, v206
	s_nop 0
	v_mul_f32_e32 v80, v80, v206
	v_mul_f32_e32 v206, v137, v80
.LBB0_1062:
	s_or_b64 exec, exec, s[0:1]
	v_bfe_u32 v80, v206, 16, 1
	v_add3_u32 v80, v206, v80, s76
	ds_write_b16_d16_hi v138, v80 offset:128
	s_nop 0
	v_cmp_le_i32_e32 vcc, v227, v233
	s_and_saveexec_b64 s[0:1], vcc
	s_cbranch_execz .LBB0_1064
	v_sub_f32_e32 v80, v209, v136
	v_mul_f32_e32 v80, 0x3fb8aa3b, v80
	v_exp_f32_e32 v80, v80
	s_nop 0
	v_mul_f32_e32 v80, v81, v80
	v_mul_f32_e32 v214, v137, v80
.LBB0_1064:
	s_or_b64 exec, exec, s[0:1]
	v_bfe_u32 v80, v214, 16, 1
	v_add3_u32 v80, v214, v80, s76
	ds_write_b16_d16_hi v140, v80 offset:128
	s_nop 0
	v_cmp_le_i32_e32 vcc, v227, v230
	v_mov_b32_e32 v80, 0
	v_mov_b32_e32 v81, 0
	s_and_saveexec_b64 s[0:1], vcc
	s_cbranch_execz .LBB0_1066
	v_sub_f32_e32 v81, v210, v136
	v_mul_f32_e32 v81, 0x3fb8aa3b, v81
	v_exp_f32_e32 v81, v81
	s_nop 0
	v_mul_f32_e32 v81, v82, v81
	v_mul_f32_e32 v81, v137, v81
.LBB0_1066:
	s_or_b64 exec, exec, s[0:1]
	v_bfe_u32 v82, v81, 16, 1
	v_add3_u32 v81, v81, v82, s76
	ds_write_b16_d16_hi v144, v81 offset:128
	s_nop 0
	v_cmp_le_i32_e32 vcc, v227, v229
	s_and_saveexec_b64 s[0:1], vcc
	s_cbranch_execz .LBB0_1068
	v_sub_f32_e32 v80, v211, v136
	v_mul_f32_e32 v80, 0x3fb8aa3b, v80
	v_exp_f32_e32 v80, v80
	s_nop 0
	v_mul_f32_e32 v80, v83, v80
	v_mul_f32_e32 v80, v137, v80
.LBB0_1068:
	s_or_b64 exec, exec, s[0:1]
	v_bfe_u32 v81, v80, 16, 1
	v_add3_u32 v80, v80, v81, s76
	v_mad_i32_i24 v227, v232, -1, v228
	ds_write_b16_d16_hi v146, v80 offset:128
	s_nop 0
	v_cmp_ge_i32_e32 vcc, 0, v227
	v_mov_b32_e32 v80, 0
	v_mov_b32_e32 v81, 0
	s_and_saveexec_b64 s[0:1], vcc
	s_cbranch_execz .LBB0_1070
	v_sub_f32_e32 v81, v212, v136
	v_mul_f32_e32 v81, 0x3fb8aa3b, v81
	v_exp_f32_e32 v81, v81
	s_nop 0
	v_mul_f32_e32 v81, v84, v81
	v_mul_f32_e32 v81, v137, v81
.LBB0_1070:
	s_or_b64 exec, exec, s[0:1]
	v_bfe_u32 v82, v81, 16, 1
	v_add3_u32 v81, v81, v82, s76
	ds_write_b16_d16_hi v148, v81 offset:128
	s_nop 0
	v_cmp_le_i32_e32 vcc, v227, v233
	s_and_saveexec_b64 s[0:1], vcc
	s_cbranch_execz .LBB0_1072
	v_sub_f32_e32 v80, v213, v136
	v_mul_f32_e32 v80, 0x3fb8aa3b, v80
	v_exp_f32_e32 v80, v80
	s_nop 0
	v_mul_f32_e32 v80, v85, v80
	v_mul_f32_e32 v80, v137, v80
.LBB0_1072:
	s_or_b64 exec, exec, s[0:1]
	v_bfe_u32 v81, v80, 16, 1
	v_add3_u32 v80, v80, v81, s76
	ds_write_b16_d16_hi v150, v80 offset:128
	s_nop 0
	v_cmp_le_i32_e32 vcc, v227, v230
	v_mov_b32_e32 v80, 0
	v_mov_b32_e32 v81, 0
	s_and_saveexec_b64 s[0:1], vcc
	s_cbranch_execz .LBB0_1074
	v_sub_f32_e32 v81, v219, v136
	v_mul_f32_e32 v81, 0x3fb8aa3b, v81
	v_exp_f32_e32 v81, v81
	s_nop 0
	v_mul_f32_e32 v81, v86, v81
	v_mul_f32_e32 v81, v137, v81
.LBB0_1074:
	s_or_b64 exec, exec, s[0:1]
	v_bfe_u32 v82, v81, 16, 1
	v_add3_u32 v81, v81, v82, s76
	ds_write_b16_d16_hi v152, v81 offset:128
	s_nop 0
	v_cmp_le_i32_e32 vcc, v227, v229
	s_and_saveexec_b64 s[0:1], vcc
	s_cbranch_execz .LBB0_1076
	v_sub_f32_e32 v80, v220, v136
	v_mul_f32_e32 v80, 0x3fb8aa3b, v80
	v_exp_f32_e32 v80, v80
	s_nop 0
	v_mul_f32_e32 v80, v87, v80
	v_mul_f32_e32 v80, v137, v80
.LBB0_1076:
	s_or_b64 exec, exec, s[0:1]
	v_bfe_u32 v81, v80, 16, 1
	v_add3_u32 v80, v80, v81, s76
	v_mad_i32_i24 v227, v232, -2, v228
	ds_write_b16_d16_hi v154, v80 offset:128
	s_nop 0
	v_cmp_ge_i32_e32 vcc, 0, v227
	v_mov_b32_e32 v80, 0
	v_mov_b32_e32 v81, 0
	s_and_saveexec_b64 s[0:1], vcc
	s_cbranch_execz .LBB0_1078
	v_sub_f32_e32 v81, v221, v136
	v_mul_f32_e32 v81, 0x3fb8aa3b, v81
	v_exp_f32_e32 v81, v81
	s_nop 0
	v_mul_f32_e32 v81, v88, v81
	v_mul_f32_e32 v81, v137, v81
.LBB0_1078:
	s_or_b64 exec, exec, s[0:1]
	v_bfe_u32 v82, v81, 16, 1
	v_add3_u32 v81, v81, v82, s76
	ds_write_b16_d16_hi v156, v81 offset:128
	s_nop 0
	v_cmp_le_i32_e32 vcc, v227, v233
	s_and_saveexec_b64 s[0:1], vcc
	s_cbranch_execz .LBB0_1080
	v_sub_f32_e32 v80, v222, v136
	v_mul_f32_e32 v80, 0x3fb8aa3b, v80
	v_exp_f32_e32 v80, v80
	s_nop 0
	v_mul_f32_e32 v80, v89, v80
	v_mul_f32_e32 v80, v137, v80
.LBB0_1080:
	s_or_b64 exec, exec, s[0:1]
	v_bfe_u32 v81, v80, 16, 1
	v_add3_u32 v80, v80, v81, s76
	ds_write_b16_d16_hi v199, v80 offset:128
	s_nop 0
	v_cmp_le_i32_e32 vcc, v227, v230
	v_mov_b32_e32 v80, 0
	v_mov_b32_e32 v81, 0
	s_and_saveexec_b64 s[0:1], vcc
	s_cbranch_execz .LBB0_1082
	v_sub_f32_e32 v81, v223, v136
	v_mul_f32_e32 v81, 0x3fb8aa3b, v81
	v_exp_f32_e32 v81, v81
	s_nop 0
	v_mul_f32_e32 v81, v90, v81
	v_mul_f32_e32 v81, v137, v81
; DI u16 f2bf(float x) { u32 u = __float_as_uint(x); u += 0x7fffu + ((u >> 16) & 1u); return (u16)(u >> 16); }
; DI void ssd_item(const Params& p, int l, int it, char* smem) {
;     ...
;     for (int jb = 0; jb < 4; ++jb) {
;       const int j = jb * 32 + l32v;
;       const float aj = fa[j], dtj = fdt[j];
; #pragma unroll
;       for (int r = 0; r < 16; ++r) {
;         const int i = w * 32 + (r & 3) + 8 * (r >> 2) + 4 * hv_;
;         const float ai = fa[i];
;         const bool valid = dir ? (j >= i) : (j <= i);
;         const float v = valid ? acc[jb][r] * __expf(ai - aj) * dtj : 0.f;
;         BG[i * 136 + j] = f2bf(v);
;       }
.LBB0_1082:
	s_or_b64 exec, exec, s[0:1]
	v_bfe_u32 v82, v81, 16, 1
	v_add3_u32 v81, v81, v82, s76
	ds_write_b16_d16_hi v241, v81 offset:128
	s_nop 0
	v_cmp_le_i32_e32 vcc, v227, v229
	s_and_saveexec_b64 s[0:1], vcc
	s_cbranch_execz .LBB0_1084
	v_sub_f32_e32 v80, v224, v136
	v_mul_f32_e32 v80, 0x3fb8aa3b, v80
	v_exp_f32_e32 v80, v80
	s_nop 0
	v_mul_f32_e32 v80, v91, v80
	v_mul_f32_e32 v80, v137, v80
.LBB0_1084:
	s_or_b64 exec, exec, s[0:1]
	v_bfe_u32 v81, v80, 16, 1
	v_add3_u32 v80, v80, v81, s76
	v_mad_i32_i24 v227, v232, -3, v228
	ds_write_b16_d16_hi v243, v80 offset:128
	s_nop 0
	v_cmp_ge_i32_e32 vcc, 0, v227
	v_mov_b32_e32 v80, 0
	v_mov_b32_e32 v81, 0
	s_and_saveexec_b64 s[0:1], vcc
	s_cbranch_execz .LBB0_1086
	v_sub_f32_e32 v81, v225, v136
	v_mul_f32_e32 v81, 0x3fb8aa3b, v81
	v_exp_f32_e32 v81, v81
	s_nop 0
	v_mul_f32_e32 v81, v92, v81
	v_mul_f32_e32 v81, v137, v81
.LBB0_1086:
	s_or_b64 exec, exec, s[0:1]
	v_bfe_u32 v82, v81, 16, 1
	v_add3_u32 v81, v81, v82, s76
	ds_write_b16_d16_hi v245, v81 offset:128
	s_nop 0
	v_cmp_le_i32_e32 vcc, v227, v233
	s_and_saveexec_b64 s[0:1], vcc
	s_cbranch_execz .LBB0_1088
	v_sub_f32_e32 v80, v226, v136
	v_mul_f32_e32 v80, 0x3fb8aa3b, v80
	v_exp_f32_e32 v80, v80
	s_nop 0
	v_mul_f32_e32 v80, v93, v80
	v_mul_f32_e32 v80, v137, v80
.LBB0_1088:
	s_or_b64 exec, exec, s[0:1]
	v_bfe_u32 v81, v80, 16, 1
	v_add3_u32 v80, v80, v81, s76
	ds_write_b16_d16_hi v247, v80 offset:128
	s_nop 0
	v_cmp_le_i32_e32 vcc, v227, v230
	v_mov_b32_e32 v80, 0
	v_mov_b32_e32 v81, 0
	s_and_saveexec_b64 s[0:1], vcc
	s_cbranch_execz .LBB0_1090
	v_sub_f32_e32 v81, v202, v136
	v_mul_f32_e32 v81, 0x3fb8aa3b, v81
	v_exp_f32_e32 v81, v81
	s_nop 0
	v_mul_f32_e32 v81, v94, v81
	v_mul_f32_e32 v81, v137, v81
.LBB0_1090:
	s_or_b64 exec, exec, s[0:1]
	v_bfe_u32 v82, v81, 16, 1
	v_add3_u32 v81, v81, v82, s76
	ds_write_b16_d16_hi v249, v81 offset:128
	s_nop 0
	v_cmp_le_i32_e32 vcc, v227, v229
	s_and_saveexec_b64 s[0:1], vcc
	s_cbranch_execz .LBB0_1092
	v_sub_f32_e32 v80, v203, v136
	v_mul_f32_e32 v80, 0x3fb8aa3b, v80
	v_exp_f32_e32 v80, v80
	s_nop 0
	v_mul_f32_e32 v80, v95, v80
	v_mul_f32_e32 v80, v137, v80
.LBB0_1092:
	s_or_b64 exec, exec, s[0:1]
	v_bfe_u32 v81, v80, 16, 1
	v_add3_u32 v80, v80, v81, s76
	ds_write_b16_d16_hi v250, v80 offset:128
	v_add_u32_e32 v82, 0x60, v128
	v_sub_u32_e32 v228, v82, v130
	v_mul_i32_i24_e32 v228, v228, v233
	v_mad_i32_i24 v227, v232, 0, v228
	ds_read2st64_b32 v[80:81], v251 offset0:205 offset1:207
	s_nop 0
	v_cmp_ge_i32_e32 vcc, 0, v227
	v_mov_b32_e32 v83, 0
	v_mov_b32_e32 v84, 0
	s_waitcnt lgkmcnt(0)
	s_and_saveexec_b64 s[0:1], vcc
	s_cbranch_execz .LBB0_1094
	v_sub_f32_e32 v84, v208, v80
	v_mul_f32_e32 v84, 0x3fb8aa3b, v84
	v_exp_f32_e32 v84, v84
	s_nop 0
	v_mul_f32_e32 v64, v64, v84
	v_mul_f32_e32 v84, v81, v64
.LBB0_1094:
	s_or_b64 exec, exec, s[0:1]
	v_bfe_u32 v64, v84, 16, 1
	v_add3_u32 v64, v84, v64, s76
	ds_write_b16_d16_hi v138, v64 offset:192
	s_nop 0
	v_cmp_le_i32_e32 vcc, v227, v233
	s_and_saveexec_b64 s[0:1], vcc
	s_cbranch_execz .LBB0_1096
	v_sub_f32_e32 v64, v209, v80
	v_mul_f32_e32 v64, 0x3fb8aa3b, v64
	v_exp_f32_e32 v64, v64
	s_nop 0
	v_mul_f32_e32 v64, v65, v64
	v_mul_f32_e32 v83, v81, v64
.LBB0_1096:
	s_or_b64 exec, exec, s[0:1]
	v_bfe_u32 v64, v83, 16, 1
	v_add3_u32 v64, v83, v64, s76
	ds_write_b16_d16_hi v140, v64 offset:192
	s_nop 0
	v_cmp_le_i32_e32 vcc, v227, v230
	v_mov_b32_e32 v64, 0
	v_mov_b32_e32 v65, 0
	s_and_saveexec_b64 s[0:1], vcc
	s_cbranch_execz .LBB0_1098
	v_sub_f32_e32 v65, v210, v80
	v_mul_f32_e32 v65, 0x3fb8aa3b, v65
	v_exp_f32_e32 v65, v65
	s_nop 0
	v_mul_f32_e32 v65, v66, v65
	v_mul_f32_e32 v65, v81, v65
.LBB0_1098:
	s_or_b64 exec, exec, s[0:1]
	v_bfe_u32 v66, v65, 16, 1
	v_add3_u32 v65, v65, v66, s76
	ds_write_b16_d16_hi v144, v65 offset:192
	s_nop 0
	v_cmp_le_i32_e32 vcc, v227, v229
	s_and_saveexec_b64 s[0:1], vcc
	s_cbranch_execz .LBB0_1100
	v_sub_f32_e32 v64, v211, v80
	v_mul_f32_e32 v64, 0x3fb8aa3b, v64
	v_exp_f32_e32 v64, v64
	s_nop 0
	v_mul_f32_e32 v64, v67, v64
	v_mul_f32_e32 v64, v81, v64
.LBB0_1100:
	s_or_b64 exec, exec, s[0:1]
	v_bfe_u32 v65, v64, 16, 1
	v_add3_u32 v64, v64, v65, s76
	v_mad_i32_i24 v227, v232, -1, v228
	ds_write_b16_d16_hi v146, v64 offset:192
	s_nop 0
	v_cmp_ge_i32_e32 vcc, 0, v227
	v_mov_b32_e32 v64, 0
	v_mov_b32_e32 v65, 0
	s_and_saveexec_b64 s[0:1], vcc
	s_cbranch_execz .LBB0_1102
	v_sub_f32_e32 v65, v212, v80
	v_mul_f32_e32 v65, 0x3fb8aa3b, v65
	v_exp_f32_e32 v65, v65
	s_nop 0
	v_mul_f32_e32 v65, v68, v65
	v_mul_f32_e32 v65, v81, v65
; DI u16 f2bf(float x) { u32 u = __float_as_uint(x); u += 0x7fffu + ((u >> 16) & 1u); return (u16)(u >> 16); }
; DI void ssd_item(const Params& p, int l, int it, char* smem) {
;     ...
;     for (int jb = 0; jb < 4; ++jb) {
;       const int j = jb * 32 + l32v;
;       const float aj = fa[j], dtj = fdt[j];
; #pragma unroll
;       for (int r = 0; r < 16; ++r) {
;         const int i = w * 32 + (r & 3) + 8 * (r >> 2) + 4 * hv_;
;         const float ai = fa[i];
;         const bool valid = dir ? (j >= i) : (j <= i);
;         const float v = valid ? acc[jb][r] * __expf(ai - aj) * dtj : 0.f;
;         BG[i * 136 + j] = f2bf(v);
;       }
.LBB0_1102:
	s_or_b64 exec, exec, s[0:1]
	v_bfe_u32 v66, v65, 16, 1
	v_add3_u32 v65, v65, v66, s76
	ds_write_b16_d16_hi v148, v65 offset:192
	s_nop 0
	v_cmp_le_i32_e32 vcc, v227, v233
	s_and_saveexec_b64 s[0:1], vcc
	s_cbranch_execz .LBB0_1104
	v_sub_f32_e32 v64, v213, v80
	v_mul_f32_e32 v64, 0x3fb8aa3b, v64
	v_exp_f32_e32 v64, v64
	s_nop 0
	v_mul_f32_e32 v64, v69, v64
	v_mul_f32_e32 v64, v81, v64
.LBB0_1104:
	s_or_b64 exec, exec, s[0:1]
	v_bfe_u32 v65, v64, 16, 1
	v_add3_u32 v64, v64, v65, s76
	ds_write_b16_d16_hi v150, v64 offset:192
	s_nop 0
	v_cmp_le_i32_e32 vcc, v227, v230
	v_mov_b32_e32 v64, 0
	v_mov_b32_e32 v65, 0
	s_and_saveexec_b64 s[0:1], vcc
	s_cbranch_execz .LBB0_1106
	v_sub_f32_e32 v65, v219, v80
	v_mul_f32_e32 v65, 0x3fb8aa3b, v65
	v_exp_f32_e32 v65, v65
	s_nop 0
	v_mul_f32_e32 v65, v70, v65
	v_mul_f32_e32 v65, v81, v65
.LBB0_1106:
	s_or_b64 exec, exec, s[0:1]
	v_bfe_u32 v66, v65, 16, 1
	v_add3_u32 v65, v65, v66, s76
	ds_write_b16_d16_hi v152, v65 offset:192
	s_nop 0
	v_cmp_le_i32_e32 vcc, v227, v229
	s_and_saveexec_b64 s[0:1], vcc
	s_cbranch_execz .LBB0_1108
	v_sub_f32_e32 v64, v220, v80
	v_mul_f32_e32 v64, 0x3fb8aa3b, v64
	v_exp_f32_e32 v64, v64
	s_nop 0
	v_mul_f32_e32 v64, v71, v64
	v_mul_f32_e32 v64, v81, v64
.LBB0_1108:
	s_or_b64 exec, exec, s[0:1]
	v_bfe_u32 v65, v64, 16, 1
	v_add3_u32 v64, v64, v65, s76
	v_mad_i32_i24 v227, v232, -2, v228
	ds_write_b16_d16_hi v154, v64 offset:192
	s_nop 0
	v_cmp_ge_i32_e32 vcc, 0, v227
	v_mov_b32_e32 v64, 0
	v_mov_b32_e32 v65, 0
	s_and_saveexec_b64 s[0:1], vcc
	s_cbranch_execz .LBB0_1110
	v_sub_f32_e32 v65, v221, v80
	v_mul_f32_e32 v65, 0x3fb8aa3b, v65
	v_exp_f32_e32 v65, v65
	s_nop 0
	v_mul_f32_e32 v65, v72, v65
	v_mul_f32_e32 v65, v81, v65
.LBB0_1110:
	s_or_b64 exec, exec, s[0:1]
	v_bfe_u32 v66, v65, 16, 1
	v_add3_u32 v65, v65, v66, s76
	ds_write_b16_d16_hi v156, v65 offset:192
	s_nop 0
	v_cmp_le_i32_e32 vcc, v227, v233
	s_and_saveexec_b64 s[0:1], vcc
	s_cbranch_execz .LBB0_1112
	v_sub_f32_e32 v64, v222, v80
	v_mul_f32_e32 v64, 0x3fb8aa3b, v64
	v_exp_f32_e32 v64, v64
	s_nop 0
	v_mul_f32_e32 v64, v73, v64
	v_mul_f32_e32 v64, v81, v64
.LBB0_1112:
	s_or_b64 exec, exec, s[0:1]
	v_bfe_u32 v65, v64, 16, 1
	v_add3_u32 v64, v64, v65, s76
	ds_write_b16_d16_hi v199, v64 offset:192
	s_nop 0
	v_cmp_le_i32_e32 vcc, v227, v230
	v_mov_b32_e32 v64, 0
	v_mov_b32_e32 v65, 0
	s_and_saveexec_b64 s[0:1], vcc
	s_cbranch_execz .LBB0_1114
	v_sub_f32_e32 v65, v223, v80
	v_mul_f32_e32 v65, 0x3fb8aa3b, v65
	v_exp_f32_e32 v65, v65
	s_nop 0
	v_mul_f32_e32 v65, v74, v65
	v_mul_f32_e32 v65, v81, v65
.LBB0_1114:
	s_or_b64 exec, exec, s[0:1]
	v_bfe_u32 v66, v65, 16, 1
	v_add3_u32 v65, v65, v66, s76
	ds_write_b16_d16_hi v241, v65 offset:192
	s_nop 0
	v_cmp_le_i32_e32 vcc, v227, v229
	s_and_saveexec_b64 s[0:1], vcc
	s_cbranch_execz .LBB0_1116
	v_sub_f32_e32 v64, v224, v80
	v_mul_f32_e32 v64, 0x3fb8aa3b, v64
	v_exp_f32_e32 v64, v64
	s_nop 0
	v_mul_f32_e32 v64, v75, v64
	v_mul_f32_e32 v64, v81, v64
.LBB0_1116:
	s_or_b64 exec, exec, s[0:1]
	v_bfe_u32 v65, v64, 16, 1
	v_add3_u32 v64, v64, v65, s76
	v_mad_i32_i24 v227, v232, -3, v228
	ds_write_b16_d16_hi v243, v64 offset:192
	s_nop 0
	v_cmp_ge_i32_e32 vcc, 0, v227
	v_mov_b32_e32 v64, 0
	v_mov_b32_e32 v65, 0
	s_and_saveexec_b64 s[0:1], vcc
	s_cbranch_execz .LBB0_1118
	v_sub_f32_e32 v65, v225, v80
	v_mul_f32_e32 v65, 0x3fb8aa3b, v65
	v_exp_f32_e32 v65, v65
	s_nop 0
	v_mul_f32_e32 v65, v76, v65
	v_mul_f32_e32 v65, v81, v65
.LBB0_1118:
	s_or_b64 exec, exec, s[0:1]
	v_bfe_u32 v66, v65, 16, 1
	v_add3_u32 v65, v65, v66, s76
	ds_write_b16_d16_hi v245, v65 offset:192
	s_nop 0
	v_cmp_le_i32_e32 vcc, v227, v233
	s_and_saveexec_b64 s[0:1], vcc
	s_cbranch_execz .LBB0_1120
	v_sub_f32_e32 v64, v226, v80
	v_mul_f32_e32 v64, 0x3fb8aa3b, v64
	v_exp_f32_e32 v64, v64
	s_nop 0
	v_mul_f32_e32 v64, v77, v64
	v_mul_f32_e32 v64, v81, v64
.LBB0_1120:
	s_or_b64 exec, exec, s[0:1]
	v_bfe_u32 v65, v64, 16, 1
	v_add3_u32 v64, v64, v65, s76
	ds_write_b16_d16_hi v247, v64 offset:192
	s_nop 0
	v_cmp_le_i32_e32 vcc, v227, v230
	v_mov_b32_e32 v64, 0
	v_mov_b32_e32 v65, 0
	s_and_saveexec_b64 s[0:1], vcc
	s_cbranch_execz .LBB0_1122
	v_sub_f32_e32 v65, v202, v80
	v_mul_f32_e32 v65, 0x3fb8aa3b, v65
	v_exp_f32_e32 v65, v65
	s_nop 0
	v_mul_f32_e32 v65, v78, v65
	v_mul_f32_e32 v65, v81, v65
.LBB0_1122:
	s_or_b64 exec, exec, s[0:1]
	v_bfe_u32 v66, v65, 16, 1
	v_add3_u32 v65, v65, v66, s76
	ds_write_b16_d16_hi v249, v65 offset:192
	s_nop 0
	v_cmp_le_i32_e32 vcc, v227, v229
	s_and_saveexec_b64 s[0:1], vcc
	s_cbranch_execz .LBB0_983
	v_sub_f32_e32 v64, v203, v80
	v_mul_f32_e32 v64, 0x3fb8aa3b, v64
	v_exp_f32_e32 v64, v64
	s_nop 0
	v_mul_f32_e32 v64, v79, v64
	v_mul_f32_e32 v64, v81, v64
	s_branch .LBB0_983
